# v39 + same dot-chain merge in the prompt-scan (R=1) step loop, and the last remaining merge in the R=2 loop
# speedup vs baseline: 1.0084x; 1.0011x over previous
; __device__ __forceinline__ float red4(float v) { v += dppf<0xB1>(v); v += dppf<0x4E>(v); return v; }
; __device__ __forceinline__ float red8(float v) { v = red4(v); v += dppf<0x141>(v); return v; }
; template <int R, int DEFY> __forceinline__
; __device__ __forceinline__ void scan_chain(const Params& p, int j, int seq_start, int len, int h, int dir, int gtid, float* lds  , bool do_steps, bool do_prep, int row_base, int nrows) {
;     ...
;         auto cstep = [&](int s, const VS& d) {
;             float yo[R];
; #pragma unroll
;             for (int r = 0; r < R; ++r) {
;                 f2 sacc = {0.f, 0.f}, sacc2 = {0.f, 0.f};
; #pragma unroll
;                 for (int q = 0; q < NQ; ++q) {
;                     sacc = st2[r][2 * q] * __builtin_shufflevector(d.kk[q], d.kk[q], 0, 1) + sacc;
;                     sacc2 = st2[r][2 * q + 1] * __builtin_shufflevector(d.kk[q], d.kk[q], 2, 3) + sacc2;
;                 }
;                 sacc = sacc + sacc2;
;                 float sa = sacc.x + sacc.y;
;                 sa = red8(sa);
;                 const f2 sa2 = {sa, sa}, v2 = {d.vv[r], d.vv[r]};
;                 f2 yacc = {0.f, 0.f}, yacc2 = {0.f, 0.f};
; #pragma unroll
;                 for (int q = 0; q < NQ; ++q) {
;                     const f2 t0 = v2 * __builtin_shufflevector(d.kd[q], d.kd[q], 0, 1) - sa2 * __builtin_shufflevector(d.ka[q], d.ka[q], 0, 1);
;                     const f2 t1 = v2 * __builtin_shufflevector(d.kd[q], d.kd[q], 2, 3) - sa2 * __builtin_shufflevector(d.ka[q], d.ka[q], 2, 3);
;                     st2[r][2 * q] = st2[r][2 * q] * __builtin_shufflevector(d.w[q], d.w[q], 0, 1) + t0;
;                     st2[r][2 * q + 1] = st2[r][2 * q + 1] * __builtin_shufflevector(d.w[q], d.w[q], 2, 3) + t1;
;                     yacc = st2[r][2 * q] * __builtin_shufflevector(d.rr[q], d.rr[q], 0, 1) + yacc;
;                     yacc2 = st2[r][2 * q + 1] * __builtin_shufflevector(d.rr[q], d.rr[q], 2, 3) + yacc2;
;                 }
;                 yacc = yacc + yacc2;
;                 yo[r] = (DEFY == 1) ? (yacc.x + yacc.y) : ((DEFY == 2) ? red4(yacc.x + yacc.y) : red8(yacc.x + yacc.y));
;             }
.LBB0_76:
	s_waitcnt lgkmcnt(10)
	v_pk_fma_f32 v[90:91], v[140:141], v[20:21], 0 op_sel_hi:[1,1,0]
	v_pk_fma_f32 v[156:157], v[138:139], v[22:23], v[90:91]
	v_pk_fma_f32 v[20:21], v[76:77], v[20:21], 0 op_sel_hi:[1,1,0]
	v_pk_fma_f32 v[22:23], v[58:59], v[22:23], v[20:21]
	s_waitcnt lgkmcnt(9)
	v_pk_fma_f32 v[20:21], v[56:57], v[24:25], v[22:23]
	v_pk_fma_f32 v[22:23], v[52:53], v[26:27], v[20:21]
	v_pk_fma_f32 v[90:91], v[136:137], v[24:25], v[156:157]
	v_pk_fma_f32 v[156:157], v[130:131], v[26:27], v[90:91]
	v_add_f32_e32 v20, v22, v23
	v_add_f32_e32 v90, v156, v157
	ds_read_b128 v[60:63], v200
	ds_read_b128 v[64:67], v200 offset:16
	ds_read_b128 v[68:71], v200 offset:256
	ds_read_b128 v[72:75], v200 offset:272
	ds_read_b128 v[78:81], v200 offset:512
	ds_read_b128 v[82:85], v200 offset:528
	ds_read_b128 v[86:89], v200 offset:768
	ds_read_b128 v[144:147], v200 offset:784
	ds_read_b128 v[148:151], v200 offset:1024
	ds_read_b128 v[152:155], v200 offset:1040
	ds_read_b64 v[54:55], v199
	v_add_f32_dpp v20, v20, v20 quad_perm:[1,0,3,2] row_mask:0xf bank_mask:0xf bound_ctrl:1
	v_add_f32_dpp v90, v90, v90 quad_perm:[1,0,3,2] row_mask:0xf bank_mask:0xf bound_ctrl:1
	s_cmp_gt_u32 s17, 11
	v_add_f32_dpp v20, v20, v20 quad_perm:[2,3,0,1] row_mask:0xf bank_mask:0xf bound_ctrl:1
	v_add_f32_dpp v90, v90, v90 quad_perm:[2,3,0,1] row_mask:0xf bank_mask:0xf bound_ctrl:1
	s_cselect_b64 s[30:31], -1, 0
	v_add_f32_dpp v20, v20, v20 row_half_mirror row_mask:0xf bank_mask:0xf bound_ctrl:1
	v_add_f32_dpp v90, v90, v90 row_half_mirror row_mask:0xf bank_mask:0xf bound_ctrl:1
	s_waitcnt lgkmcnt(14)
	v_pk_mul_f32 v[22:23], v[32:33], v[20:21] op_sel_hi:[1,0]
	v_pk_mul_f32 v[156:157], v[32:33], v[90:91] op_sel_hi:[1,0]
	v_pk_mul_f32 v[160:161], v[34:35], v[90:91] op_sel_hi:[1,0]
	s_waitcnt lgkmcnt(11)
	v_pk_fma_f32 v[22:23], v[44:45], v[142:143], v[22:23] op_sel:[0,1,0] neg_lo:[0,0,1] neg_hi:[0,0,1]
	v_pk_mul_f32 v[24:25], v[34:35], v[20:21] op_sel_hi:[1,0]
	v_pk_fma_f32 v[156:157], v[44:45], v[142:143], v[156:157] op_sel_hi:[1,0,1] neg_lo:[0,0,1] neg_hi:[0,0,1]
	v_pk_fma_f32 v[160:161], v[46:47], v[142:143], v[160:161] op_sel_hi:[1,0,1] neg_lo:[0,0,1] neg_hi:[0,0,1]
	v_pk_mul_f32 v[162:163], v[28:29], v[90:91] op_sel_hi:[1,0]
	v_pk_mul_f32 v[90:91], v[30:31], v[90:91] op_sel_hi:[1,0]
	v_pk_fma_f32 v[24:25], v[46:47], v[142:143], v[24:25] op_sel:[0,1,0] neg_lo:[0,0,1] neg_hi:[0,0,1]
	v_pk_fma_f32 v[76:77], v[76:77], v[12:13], v[22:23]
	v_pk_mul_f32 v[22:23], v[28:29], v[20:21] op_sel_hi:[1,0]
	v_pk_mul_f32 v[20:21], v[30:31], v[20:21] op_sel_hi:[1,0]
	v_pk_fma_f32 v[140:141], v[140:141], v[12:13], v[156:157]
	v_pk_fma_f32 v[138:139], v[138:139], v[14:15], v[160:161]
	v_pk_fma_f32 v[162:163], v[36:37], v[142:143], v[162:163] op_sel_hi:[1,0,1] neg_lo:[0,0,1] neg_hi:[0,0,1]
	v_pk_fma_f32 v[90:91], v[38:39], v[142:143], v[90:91] op_sel_hi:[1,0,1] neg_lo:[0,0,1] neg_hi:[0,0,1]
	v_pk_fma_f32 v[58:59], v[58:59], v[14:15], v[24:25]
	v_pk_fma_f32 v[22:23], v[36:37], v[142:143], v[22:23] op_sel:[0,1,0] neg_lo:[0,0,1] neg_hi:[0,0,1]
	v_pk_fma_f32 v[20:21], v[38:39], v[142:143], v[20:21] op_sel:[0,1,0] neg_lo:[0,0,1] neg_hi:[0,0,1]
	v_pk_fma_f32 v[156:157], v[48:49], v[140:141], 0 op_sel_hi:[1,1,0]
	v_pk_fma_f32 v[160:161], v[50:51], v[138:139], v[156:157]
	v_pk_fma_f32 v[136:137], v[136:137], v[16:17], v[162:163]
	v_pk_fma_f32 v[90:91], v[130:131], v[18:19], v[90:91]
	v_pk_fma_f32 v[12:13], v[48:49], v[76:77], 0 op_sel_hi:[1,1,0]
	v_pk_fma_f32 v[14:15], v[50:51], v[58:59], v[12:13]
	v_pk_fma_f32 v[56:57], v[56:57], v[16:17], v[22:23]
	v_pk_fma_f32 v[52:53], v[52:53], v[18:19], v[20:21]
	v_pk_fma_f32 v[130:131], v[40:41], v[136:137], v[160:161]
	v_pk_fma_f32 v[156:157], v[42:43], v[90:91], v[130:131]
	v_pk_fma_f32 v[12:13], v[40:41], v[56:57], v[14:15]
	v_pk_fma_f32 v[14:15], v[42:43], v[52:53], v[12:13]
	v_add_f32_e32 v130, v156, v157
	v_add_f32_e32 v12, v14, v15
	s_waitcnt lgkmcnt(10)
	v_pk_fma_f32 v[156:157], v[62:63], v[138:139], 0 op_sel_hi:[1,1,0]
	v_add_f32_dpp v130, v130, v130 quad_perm:[1,0,3,2] row_mask:0xf bank_mask:0xf bound_ctrl:1
	v_add_f32_dpp v12, v12, v12 quad_perm:[1,0,3,2] row_mask:0xf bank_mask:0xf bound_ctrl:1
	s_waitcnt lgkmcnt(9)
	v_pk_fma_f32 v[156:157], v[66:67], v[90:91], v[156:157]
	v_add_f32_dpp v130, v130, v130 quad_perm:[2,3,0,1] row_mask:0xf bank_mask:0xf bound_ctrl:1
	v_add_f32_dpp v12, v12, v12 quad_perm:[2,3,0,1] row_mask:0xf bank_mask:0xf bound_ctrl:1
	ds_write2_b32 v132, v130, v12 offset1:2
	v_pk_fma_f32 v[130:131], v[60:61], v[140:141], v[156:157]
	v_pk_fma_f32 v[60:61], v[60:61], v[76:77], 0 op_sel_hi:[1,1,0]
	v_pk_fma_f32 v[130:131], v[64:65], v[136:137], v[130:131]
	v_pk_fma_f32 v[62:63], v[62:63], v[58:59], v[60:61]
	v_pk_fma_f32 v[60:61], v[64:65], v[56:57], v[62:63]
	v_add_f32_e32 v130, v130, v131
	v_pk_fma_f32 v[62:63], v[66:67], v[52:53], v[60:61]
	ds_read_b128 v[20:23], v200 offset:1536
	ds_read_b128 v[24:27], v200 offset:1552
	ds_read_b128 v[12:15], v200 offset:1792
	ds_read_b128 v[16:19], v200 offset:1808
	ds_read_b128 v[32:35], v200 offset:2048
	ds_read_b128 v[28:31], v200 offset:2064
	ds_read_b128 v[44:47], v200 offset:2304
	ds_read_b128 v[36:39], v200 offset:2320
	ds_read_b128 v[48:51], v200 offset:2560
	ds_read_b128 v[40:43], v200 offset:2576
	ds_read_b64 v[142:143], v199 offset:1536
	v_add_f32_dpp v130, v130, v130 quad_perm:[1,0,3,2] row_mask:0xf bank_mask:0xf bound_ctrl:1
	v_add_u32_e32 v201, 0x400, v132
	v_add_f32_dpp v130, v130, v130 quad_perm:[2,3,0,1] row_mask:0xf bank_mask:0xf bound_ctrl:1
	v_add_f32_e32 v60, v62, v63
	s_and_b64 vcc, exec, s[30:31]
	v_add_f32_dpp v130, v130, v130 row_half_mirror row_mask:0xf bank_mask:0xf bound_ctrl:1
	s_waitcnt lgkmcnt(14)
; __device__ __forceinline__ float red4(float v) { v += dppf<0xB1>(v); v += dppf<0x4E>(v); return v; }
; __device__ __forceinline__ float red8(float v) { v = red4(v); v += dppf<0x141>(v); return v; }
; template <int R, int DEFY> __forceinline__
; __device__ __forceinline__ void scan_chain(const Params& p, int j, int seq_start, int len, int h, int dir, int gtid, float* lds  , bool do_steps, bool do_prep, int row_base, int nrows) {
;     ...
;         auto cstep = [&](int s, const VS& d) {
;             float yo[R];
; #pragma unroll
;             for (int r = 0; r < R; ++r) {
;                 f2 sacc = {0.f, 0.f}, sacc2 = {0.f, 0.f};
; #pragma unroll
;                 for (int q = 0; q < NQ; ++q) {
;                     sacc = st2[r][2 * q] * __builtin_shufflevector(d.kk[q], d.kk[q], 0, 1) + sacc;
;                     sacc2 = st2[r][2 * q + 1] * __builtin_shufflevector(d.kk[q], d.kk[q], 2, 3) + sacc2;
;                 }
;                 sacc = sacc + sacc2;
;                 float sa = sacc.x + sacc.y;
;                 sa = red8(sa);
;                 const f2 sa2 = {sa, sa}, v2 = {d.vv[r], d.vv[r]};
;                 f2 yacc = {0.f, 0.f}, yacc2 = {0.f, 0.f};
; #pragma unroll
;                 for (int q = 0; q < NQ; ++q) {
;                     const f2 t0 = v2 * __builtin_shufflevector(d.kd[q], d.kd[q], 0, 1) - sa2 * __builtin_shufflevector(d.ka[q], d.ka[q], 0, 1);
;                     const f2 t1 = v2 * __builtin_shufflevector(d.kd[q], d.kd[q], 2, 3) - sa2 * __builtin_shufflevector(d.ka[q], d.ka[q], 2, 3);
;                     st2[r][2 * q] = st2[r][2 * q] * __builtin_shufflevector(d.w[q], d.w[q], 0, 1) + t0;
;                     st2[r][2 * q + 1] = st2[r][2 * q + 1] * __builtin_shufflevector(d.w[q], d.w[q], 2, 3) + t1;
;                     yacc = st2[r][2 * q] * __builtin_shufflevector(d.rr[q], d.rr[q], 0, 1) + yacc;
;                     yacc2 = st2[r][2 * q + 1] * __builtin_shufflevector(d.rr[q], d.rr[q], 2, 3) + yacc2;
;                 }
;                 yacc = yacc + yacc2;
;                 yo[r] = (DEFY == 1) ? (yacc.x + yacc.y) : ((DEFY == 2) ? red4(yacc.x + yacc.y) : red8(yacc.x + yacc.y));
;             }
	v_pk_mul_f32 v[156:157], v[78:79], v[130:131] op_sel_hi:[1,0]
	v_pk_mul_f32 v[160:161], v[80:81], v[130:131] op_sel_hi:[1,0]
	s_waitcnt lgkmcnt(12)
	v_pk_fma_f32 v[156:157], v[86:87], v[54:55], v[156:157] op_sel_hi:[1,0,1] neg_lo:[0,0,1] neg_hi:[0,0,1]
	v_pk_fma_f32 v[160:161], v[88:89], v[54:55], v[160:161] op_sel_hi:[1,0,1] neg_lo:[0,0,1] neg_hi:[0,0,1]
	v_pk_mul_f32 v[162:163], v[82:83], v[130:131] op_sel_hi:[1,0]
	v_pk_mul_f32 v[130:131], v[84:85], v[130:131] op_sel_hi:[1,0]
	v_pk_fma_f32 v[140:141], v[68:69], v[140:141], v[156:157]
	v_pk_fma_f32 v[138:139], v[70:71], v[138:139], v[160:161]
	v_pk_fma_f32 v[162:163], v[144:145], v[54:55], v[162:163] op_sel_hi:[1,0,1] neg_lo:[0,0,1] neg_hi:[0,0,1]
	v_pk_fma_f32 v[130:131], v[146:147], v[54:55], v[130:131] op_sel_hi:[1,0,1] neg_lo:[0,0,1] neg_hi:[0,0,1]
	v_pk_fma_f32 v[156:157], v[148:149], v[140:141], 0 op_sel_hi:[1,1,0]
	v_pk_fma_f32 v[160:161], v[150:151], v[138:139], v[156:157]
	v_pk_fma_f32 v[162:163], v[72:73], v[136:137], v[162:163]
	v_pk_fma_f32 v[168:169], v[74:75], v[90:91], v[130:131]
	v_pk_fma_f32 v[90:91], v[152:153], v[162:163], v[160:161]
	v_pk_fma_f32 v[130:131], v[154:155], v[168:169], v[90:91]
	v_add_f32_dpp v60, v60, v60 quad_perm:[1,0,3,2] row_mask:0xf bank_mask:0xf bound_ctrl:1
	v_add_f32_e32 v90, v130, v131
	s_waitcnt lgkmcnt(10)
	v_pk_fma_f32 v[130:131], v[20:21], v[140:141], 0 op_sel_hi:[1,1,0]
	v_pk_fma_f32 v[136:137], v[22:23], v[138:139], v[130:131]
	v_add_f32_dpp v60, v60, v60 quad_perm:[2,3,0,1] row_mask:0xf bank_mask:0xf bound_ctrl:1
	s_waitcnt lgkmcnt(9)
	v_pk_fma_f32 v[130:131], v[24:25], v[162:163], v[136:137]
	v_pk_fma_f32 v[136:137], v[26:27], v[168:169], v[130:131]
	v_add_f32_dpp v60, v60, v60 row_half_mirror row_mask:0xf bank_mask:0xf bound_ctrl:1
	v_pk_mul_f32 v[64:65], v[80:81], v[60:61] op_sel_hi:[1,0]
	v_add_f32_e32 v130, v136, v137
	v_pk_fma_f32 v[64:65], v[88:89], v[54:55], v[64:65] op_sel:[0,1,0] neg_lo:[0,0,1] neg_hi:[0,0,1]
	v_pk_mul_f32 v[62:63], v[78:79], v[60:61] op_sel_hi:[1,0]
	v_add_f32_dpp v130, v130, v130 quad_perm:[1,0,3,2] row_mask:0xf bank_mask:0xf bound_ctrl:1
	v_pk_fma_f32 v[160:161], v[70:71], v[58:59], v[64:65]
	v_pk_mul_f32 v[64:65], v[82:83], v[60:61] op_sel_hi:[1,0]
	v_pk_mul_f32 v[60:61], v[84:85], v[60:61] op_sel_hi:[1,0]
	v_add_f32_dpp v130, v130, v130 quad_perm:[2,3,0,1] row_mask:0xf bank_mask:0xf bound_ctrl:1
	v_pk_fma_f32 v[62:63], v[86:87], v[54:55], v[62:63] op_sel:[0,1,0] neg_lo:[0,0,1] neg_hi:[0,0,1]
	v_pk_fma_f32 v[64:65], v[144:145], v[54:55], v[64:65] op_sel:[0,1,0] neg_lo:[0,0,1] neg_hi:[0,0,1]
	v_pk_fma_f32 v[54:55], v[146:147], v[54:55], v[60:61] op_sel:[0,1,0] neg_lo:[0,0,1] neg_hi:[0,0,1]
	v_add_f32_dpp v146, v130, v130 row_half_mirror row_mask:0xf bank_mask:0xf bound_ctrl:1
	v_pk_fma_f32 v[156:157], v[68:69], v[76:77], v[62:63]
	s_waitcnt lgkmcnt(6)
	v_pk_mul_f32 v[130:131], v[32:33], v[146:147] op_sel_hi:[1,0]
	v_pk_mul_f32 v[136:137], v[34:35], v[146:147] op_sel_hi:[1,0]
	v_pk_fma_f32 v[58:59], v[148:149], v[156:157], 0 op_sel_hi:[1,1,0]
	s_waitcnt lgkmcnt(0)
; template <int R, int DEFY> __forceinline__
; __device__ __forceinline__ void scan_chain(const Params& p, int j, int seq_start, int len, int h, int dir, int gtid, float* lds  , bool do_steps, bool do_prep, int row_base, int nrows) {
;     ...
;         auto cstep = [&](int s, const VS& d) {
;             float yo[R];
; #pragma unroll
;             for (int r = 0; r < R; ++r) {
;                 f2 sacc = {0.f, 0.f}, sacc2 = {0.f, 0.f};
; #pragma unroll
;                 for (int q = 0; q < NQ; ++q) {
;                     sacc = st2[r][2 * q] * __builtin_shufflevector(d.kk[q], d.kk[q], 0, 1) + sacc;
;                     sacc2 = st2[r][2 * q + 1] * __builtin_shufflevector(d.kk[q], d.kk[q], 2, 3) + sacc2;
;                 }
;                 sacc = sacc + sacc2;
;                 float sa = sacc.x + sacc.y;
;                 sa = red8(sa);
;                 const f2 sa2 = {sa, sa}, v2 = {d.vv[r], d.vv[r]};
;                 f2 yacc = {0.f, 0.f}, yacc2 = {0.f, 0.f};
; #pragma unroll
;                 for (int q = 0; q < NQ; ++q) {
;                     const f2 t0 = v2 * __builtin_shufflevector(d.kd[q], d.kd[q], 0, 1) - sa2 * __builtin_shufflevector(d.ka[q], d.ka[q], 0, 1);
;                     const f2 t1 = v2 * __builtin_shufflevector(d.kd[q], d.kd[q], 2, 3) - sa2 * __builtin_shufflevector(d.ka[q], d.ka[q], 2, 3);
;                     st2[r][2 * q] = st2[r][2 * q] * __builtin_shufflevector(d.w[q], d.w[q], 0, 1) + t0;
;                     st2[r][2 * q + 1] = st2[r][2 * q + 1] * __builtin_shufflevector(d.w[q], d.w[q], 2, 3) + t1;
;                     yacc = st2[r][2 * q] * __builtin_shufflevector(d.rr[q], d.rr[q], 0, 1) + yacc;
;                     yacc2 = st2[r][2 * q + 1] * __builtin_shufflevector(d.rr[q], d.rr[q], 2, 3) + yacc2;
;                 }
;                 yacc = yacc + yacc2;
;                 yo[r] = (DEFY == 1) ? (yacc.x + yacc.y) : ((DEFY == 2) ? red4(yacc.x + yacc.y) : red8(yacc.x + yacc.y));
;             }
;             if (DEFY == 1) {
; #pragma unroll
;                 for (int r = 0; r < R; ++r) ys[(s * 64 + row + r) * 8 + seg] = yo[r];
;             } else if (DEFY == 2) {
; #pragma unroll
;                 for (int r = 0; r < R; ++r) ys[(s * 64 + row + r) * 2 + (seg >> 2)] = yo[r];
;             } else {
; #pragma unroll
;                 for (int r = 0; r < R; ++r) ys[s * 64 + row + r] = yo[r];
;             }
	v_pk_fma_f32 v[130:131], v[44:45], v[142:143], v[130:131] op_sel_hi:[1,0,1] neg_lo:[0,0,1] neg_hi:[0,0,1]
	v_pk_fma_f32 v[136:137], v[46:47], v[142:143], v[136:137] op_sel_hi:[1,0,1] neg_lo:[0,0,1] neg_hi:[0,0,1]
	v_pk_mul_f32 v[148:149], v[28:29], v[146:147] op_sel_hi:[1,0]
	v_pk_mul_f32 v[146:147], v[30:31], v[146:147] op_sel_hi:[1,0]
	v_pk_fma_f32 v[62:63], v[150:151], v[160:161], v[58:59]
	v_pk_fma_f32 v[130:131], v[12:13], v[140:141], v[130:131]
	v_pk_fma_f32 v[136:137], v[14:15], v[138:139], v[136:137]
	v_pk_fma_f32 v[148:149], v[36:37], v[142:143], v[148:149] op_sel_hi:[1,0,1] neg_lo:[0,0,1] neg_hi:[0,0,1]
	v_pk_fma_f32 v[150:151], v[38:39], v[142:143], v[146:147] op_sel_hi:[1,0,1] neg_lo:[0,0,1] neg_hi:[0,0,1]
	v_pk_fma_f32 v[202:203], v[72:73], v[56:57], v[64:65]
	v_pk_fma_f32 v[204:205], v[74:75], v[52:53], v[54:55]
	v_pk_fma_f32 v[138:139], v[48:49], v[130:131], 0 op_sel_hi:[1,1,0]
	v_pk_fma_f32 v[140:141], v[50:51], v[136:137], v[138:139]
	v_pk_fma_f32 v[146:147], v[16:17], v[162:163], v[148:149]
	v_pk_fma_f32 v[148:149], v[18:19], v[168:169], v[150:151]
	v_pk_fma_f32 v[52:53], v[152:153], v[202:203], v[62:63]
	v_pk_fma_f32 v[54:55], v[154:155], v[204:205], v[52:53]
	v_pk_fma_f32 v[138:139], v[40:41], v[146:147], v[140:141]
	v_pk_fma_f32 v[140:141], v[42:43], v[148:149], v[138:139]
	v_add_f32_e32 v52, v54, v55
	v_add_f32_e32 v138, v140, v141
	v_add_f32_dpp v90, v90, v90 quad_perm:[1,0,3,2] row_mask:0xf bank_mask:0xf bound_ctrl:1
	v_add_f32_dpp v52, v52, v52 quad_perm:[1,0,3,2] row_mask:0xf bank_mask:0xf bound_ctrl:1
	v_add_f32_dpp v138, v138, v138 quad_perm:[1,0,3,2] row_mask:0xf bank_mask:0xf bound_ctrl:1
	v_add_f32_dpp v90, v90, v90 quad_perm:[2,3,0,1] row_mask:0xf bank_mask:0xf bound_ctrl:1
	v_add_f32_dpp v52, v52, v52 quad_perm:[2,3,0,1] row_mask:0xf bank_mask:0xf bound_ctrl:1
	v_add_f32_dpp v162, v138, v138 quad_perm:[2,3,0,1] row_mask:0xf bank_mask:0xf bound_ctrl:1
	v_pk_fma_f32 v[138:139], v[20:21], v[156:157], 0 op_sel_hi:[1,1,0]
	v_pk_fma_f32 v[140:141], v[22:23], v[160:161], v[138:139]
	ds_write2_b32 v132, v90, v52 offset0:128 offset1:130
	v_pk_fma_f32 v[138:139], v[24:25], v[202:203], v[140:141]
	v_pk_fma_f32 v[140:141], v[26:27], v[204:205], v[138:139]
	ds_read_b128 v[88:91], v200 offset:3072
	ds_read_b128 v[84:87], v200 offset:3088
	ds_read_b128 v[56:59], v200 offset:3328
	ds_read_b128 v[52:55], v200 offset:3344
	ds_read_b128 v[76:79], v200 offset:3584
	ds_read_b128 v[64:67], v200 offset:3600
	ds_read_b128 v[80:83], v200 offset:3840
	ds_read_b128 v[68:71], v200 offset:3856
	ds_read_b128 v[72:75], v200 offset:4096
	ds_read_b128 v[60:63], v200 offset:4112
	ds_read_b64 v[144:145], v199 offset:3072
	s_nop 0
	v_add_f32_e32 v138, v140, v141
	s_nop 1
	v_add_f32_dpp v138, v138, v138 quad_perm:[1,0,3,2] row_mask:0xf bank_mask:0xf bound_ctrl:1
	s_nop 1
	v_add_f32_dpp v138, v138, v138 quad_perm:[2,3,0,1] row_mask:0xf bank_mask:0xf bound_ctrl:1
	s_nop 1
	v_add_f32_dpp v138, v138, v138 row_half_mirror row_mask:0xf bank_mask:0xf bound_ctrl:1
	v_pk_mul_f32 v[140:141], v[32:33], v[138:139] op_sel_hi:[1,0]
	v_pk_mul_f32 v[150:151], v[34:35], v[138:139] op_sel_hi:[1,0]
	v_pk_fma_f32 v[140:141], v[44:45], v[142:143], v[140:141] op_sel:[0,1,0] neg_lo:[0,0,1] neg_hi:[0,0,1]
	v_pk_fma_f32 v[152:153], v[46:47], v[142:143], v[150:151] op_sel:[0,1,0] neg_lo:[0,0,1] neg_hi:[0,0,1]
	v_pk_mul_f32 v[154:155], v[28:29], v[138:139] op_sel_hi:[1,0]
	v_pk_mul_f32 v[138:139], v[30:31], v[138:139] op_sel_hi:[1,0]
	v_pk_fma_f32 v[150:151], v[12:13], v[156:157], v[140:141]
	v_pk_fma_f32 v[152:153], v[14:15], v[160:161], v[152:153]
	v_pk_fma_f32 v[154:155], v[36:37], v[142:143], v[154:155] op_sel:[0,1,0] neg_lo:[0,0,1] neg_hi:[0,0,1]
	v_pk_fma_f32 v[138:139], v[38:39], v[142:143], v[138:139] op_sel:[0,1,0] neg_lo:[0,0,1] neg_hi:[0,0,1]
	v_pk_fma_f32 v[140:141], v[48:49], v[150:151], 0 op_sel_hi:[1,1,0]
	v_pk_fma_f32 v[160:161], v[50:51], v[152:153], v[140:141]
	v_pk_fma_f32 v[154:155], v[16:17], v[202:203], v[154:155]
	v_pk_fma_f32 v[156:157], v[18:19], v[204:205], v[138:139]
	v_pk_fma_f32 v[138:139], v[40:41], v[154:155], v[160:161]
	v_pk_fma_f32 v[140:141], v[42:43], v[156:157], v[138:139]
	s_nop 0
	s_nop 0
	v_add_f32_e32 v138, v140, v141
	s_nop 1
	v_add_f32_dpp v138, v138, v138 quad_perm:[1,0,3,2] row_mask:0xf bank_mask:0xf bound_ctrl:1
	s_nop 1
	v_add_f32_dpp v138, v138, v138 quad_perm:[2,3,0,1] row_mask:0xf bank_mask:0xf bound_ctrl:1
	ds_write2_b32 v201, v162, v138 offset1:2
	s_cbranch_vccnz .LBB0_75
	ds_read_b128 v[20:23], v200 offset:4608
	ds_read_b128 v[24:27], v200 offset:4624
	ds_read_b128 v[12:15], v200 offset:4864
	ds_read_b128 v[16:19], v200 offset:4880
	ds_read_b128 v[32:35], v200 offset:5120
	ds_read_b128 v[28:31], v200 offset:5136
	ds_read_b128 v[44:47], v200 offset:5376
	ds_read_b128 v[36:39], v200 offset:5392
	ds_read_b128 v[48:51], v200 offset:5632
	ds_read_b128 v[40:43], v200 offset:5648
	ds_read_b64 v[142:143], v199 offset:4608
	s_branch .LBB0_75

; __device__ __forceinline__ float red4(float v) { v += dppf<0xB1>(v); v += dppf<0x4E>(v); return v; }
; __device__ __forceinline__ float red8(float v) { v = red4(v); v += dppf<0x141>(v); return v; }
; template <int R, int DEFY> __forceinline__
; __device__ __forceinline__ void scan_chain(const Params& p, int j, int seq_start, int len, int h, int dir, int gtid, float* lds  , bool do_steps, bool do_prep, int row_base, int nrows) {
;     ...
;         auto cstep = [&](int s, const VS& d) {
;             float yo[R];
; #pragma unroll
;             for (int r = 0; r < R; ++r) {
;                 f2 sacc = {0.f, 0.f}, sacc2 = {0.f, 0.f};
; #pragma unroll
;                 for (int q = 0; q < NQ; ++q) {
;                     sacc = st2[r][2 * q] * __builtin_shufflevector(d.kk[q], d.kk[q], 0, 1) + sacc;
;                     sacc2 = st2[r][2 * q + 1] * __builtin_shufflevector(d.kk[q], d.kk[q], 2, 3) + sacc2;
;                 }
;                 sacc = sacc + sacc2;
;                 float sa = sacc.x + sacc.y;
;                 sa = red8(sa);
;                 const f2 sa2 = {sa, sa}, v2 = {d.vv[r], d.vv[r]};
;                 f2 yacc = {0.f, 0.f}, yacc2 = {0.f, 0.f};
; #pragma unroll
;                 for (int q = 0; q < NQ; ++q) {
;                     const f2 t0 = v2 * __builtin_shufflevector(d.kd[q], d.kd[q], 0, 1) - sa2 * __builtin_shufflevector(d.ka[q], d.ka[q], 0, 1);
;                     const f2 t1 = v2 * __builtin_shufflevector(d.kd[q], d.kd[q], 2, 3) - sa2 * __builtin_shufflevector(d.ka[q], d.ka[q], 2, 3);
;                     st2[r][2 * q] = st2[r][2 * q] * __builtin_shufflevector(d.w[q], d.w[q], 0, 1) + t0;
;                     st2[r][2 * q + 1] = st2[r][2 * q + 1] * __builtin_shufflevector(d.w[q], d.w[q], 2, 3) + t1;
;                     yacc = st2[r][2 * q] * __builtin_shufflevector(d.rr[q], d.rr[q], 0, 1) + yacc;
;                     yacc2 = st2[r][2 * q + 1] * __builtin_shufflevector(d.rr[q], d.rr[q], 2, 3) + yacc2;
;                 }
;                 yacc = yacc + yacc2;
;                 yo[r] = (DEFY == 1) ? (yacc.x + yacc.y) : ((DEFY == 2) ? red4(yacc.x + yacc.y) : red8(yacc.x + yacc.y));
;             }
;             if (DEFY == 1) {
; #pragma unroll
;                 for (int r = 0; r < R; ++r) ys[(s * 64 + row + r) * 8 + seg] = yo[r];
.LBB0_95:
	s_waitcnt lgkmcnt(11)
	v_pk_fma_f32 v[88:89], v[88:89], v[136:137], 0 op_sel_hi:[1,1,0]
	v_pk_fma_f32 v[90:91], v[90:91], v[138:139], v[88:89]
	s_waitcnt lgkmcnt(10)
	v_pk_fma_f32 v[84:85], v[84:85], v[140:141], v[90:91]
	v_pk_fma_f32 v[86:87], v[86:87], v[142:143], v[84:85]
	s_add_i32 s17, s17, 4
	v_add_u32_e32 v146, 0x1800, v146
	v_add_f32_e32 v84, v86, v87
	s_andn2_b64 vcc, exec, s[88:89]
	v_add_u32_e32 v147, 0x1800, v147
	v_add_f32_dpp v84, v84, v84 quad_perm:[1,0,3,2] row_mask:0xf bank_mask:0xf bound_ctrl:1
	s_nop 1
	v_add_f32_dpp v84, v84, v84 quad_perm:[2,3,0,1] row_mask:0xf bank_mask:0xf bound_ctrl:1
	s_nop 1
	v_add_f32_dpp v84, v84, v84 row_half_mirror row_mask:0xf bank_mask:0xf bound_ctrl:1
	s_waitcnt lgkmcnt(7)
	v_pk_mul_f32 v[76:77], v[76:77], v[84:85] op_sel_hi:[1,0]
	v_pk_mul_f32 v[78:79], v[78:79], v[84:85] op_sel_hi:[1,0]
	s_waitcnt lgkmcnt(1)
	v_pk_fma_f32 v[76:77], v[80:81], v[130:131], v[76:77] op_sel_hi:[1,0,1] neg_lo:[0,0,1] neg_hi:[0,0,1]
	v_pk_fma_f32 v[78:79], v[82:83], v[130:131], v[78:79] op_sel_hi:[1,0,1] neg_lo:[0,0,1] neg_hi:[0,0,1]
	v_pk_mul_f32 v[60:61], v[60:61], v[84:85] op_sel_hi:[1,0]
	v_pk_mul_f32 v[62:63], v[62:63], v[84:85] op_sel_hi:[1,0]
	v_pk_fma_f32 v[68:69], v[68:69], v[136:137], v[76:77]
	v_pk_fma_f32 v[70:71], v[70:71], v[138:139], v[78:79]
	v_pk_fma_f32 v[60:61], v[64:65], v[130:131], v[60:61] op_sel_hi:[1,0,1] neg_lo:[0,0,1] neg_hi:[0,0,1]
	v_pk_fma_f32 v[62:63], v[66:67], v[130:131], v[62:63] op_sel_hi:[1,0,1] neg_lo:[0,0,1] neg_hi:[0,0,1]
	v_pk_fma_f32 v[72:73], v[72:73], v[68:69], 0 op_sel_hi:[1,1,0]
	v_pk_fma_f32 v[74:75], v[74:75], v[70:71], v[72:73]
	v_pk_fma_f32 v[52:53], v[52:53], v[140:141], v[60:61]
	v_pk_fma_f32 v[54:55], v[54:55], v[142:143], v[62:63]
	v_pk_fma_f32 v[56:57], v[56:57], v[52:53], v[74:75]
	v_pk_fma_f32 v[58:59], v[58:59], v[54:55], v[56:57]
	s_nop 0
	s_nop 0
	v_add_f32_e32 v56, v58, v59
	ds_write_b32 v132, v56 offset:6144
	v_add_u32_e32 v132, 0x2000, v132
	s_cbranch_vccz .LBB0_98
.LBB0_96:
	s_waitcnt lgkmcnt(10)
	v_pk_fma_f32 v[36:37], v[68:69], v[36:37], 0 op_sel_hi:[1,1,0]
	v_pk_fma_f32 v[38:39], v[70:71], v[38:39], v[36:37]
	s_waitcnt lgkmcnt(9)
	v_pk_fma_f32 v[32:33], v[52:53], v[32:33], v[38:39]
	v_pk_fma_f32 v[34:35], v[54:55], v[34:35], v[32:33]
	ds_read_b128 v[56:59], v147
	ds_read_b128 v[60:63], v147 offset:16
	ds_read_b128 v[64:67], v147 offset:256
	ds_read_b128 v[72:75], v147 offset:272
	ds_read_b128 v[76:79], v147 offset:512
	ds_read_b128 v[80:83], v147 offset:528
	ds_read_b128 v[84:87], v147 offset:768
	ds_read_b128 v[88:91], v147 offset:784
	ds_read_b128 v[136:139], v147 offset:1024
	ds_read_b128 v[140:143], v147 offset:1040
	ds_read_b32 v130, v146
	s_cmp_gt_u32 s17, 11
	v_add_f32_e32 v32, v34, v35
	s_cselect_b64 s[88:89], -1, 0
	s_and_b64 vcc, exec, s[88:89]
	v_add_f32_dpp v32, v32, v32 quad_perm:[1,0,3,2] row_mask:0xf bank_mask:0xf bound_ctrl:1
	s_nop 1
	v_add_f32_dpp v32, v32, v32 quad_perm:[2,3,0,1] row_mask:0xf bank_mask:0xf bound_ctrl:1
	s_nop 1
	v_add_f32_dpp v32, v32, v32 row_half_mirror row_mask:0xf bank_mask:0xf bound_ctrl:1
	s_waitcnt lgkmcnt(14)
	v_pk_mul_f32 v[34:35], v[40:41], v[32:33] op_sel_hi:[1,0]
	v_pk_mul_f32 v[36:37], v[42:43], v[32:33] op_sel_hi:[1,0]
	s_waitcnt lgkmcnt(11)
	v_pk_fma_f32 v[34:35], v[128:129], v[48:49], v[34:35] op_sel_hi:[0,1,1] neg_lo:[0,0,1] neg_hi:[0,0,1]
	v_pk_fma_f32 v[36:37], v[128:129], v[50:51], v[36:37] op_sel_hi:[0,1,1] neg_lo:[0,0,1] neg_hi:[0,0,1]
	v_pk_mul_f32 v[20:21], v[20:21], v[32:33] op_sel_hi:[1,0]
	v_pk_mul_f32 v[22:23], v[22:23], v[32:33] op_sel_hi:[1,0]
	v_pk_fma_f32 v[68:69], v[68:69], v[16:17], v[34:35]
	v_pk_fma_f32 v[70:71], v[70:71], v[18:19], v[36:37]
	v_pk_fma_f32 v[20:21], v[128:129], v[28:29], v[20:21] op_sel_hi:[0,1,1] neg_lo:[0,0,1] neg_hi:[0,0,1]
	v_pk_fma_f32 v[22:23], v[128:129], v[30:31], v[22:23] op_sel_hi:[0,1,1] neg_lo:[0,0,1] neg_hi:[0,0,1]
	v_pk_fma_f32 v[52:53], v[52:53], v[12:13], v[20:21]
	v_pk_fma_f32 v[54:55], v[54:55], v[14:15], v[22:23]
	s_waitcnt lgkmcnt(10)
	v_pk_fma_f32 v[56:57], v[56:57], v[68:69], 0 op_sel_hi:[1,1,0]
	v_pk_fma_f32 v[58:59], v[58:59], v[70:71], v[56:57]
	s_waitcnt lgkmcnt(9)
	v_pk_fma_f32 v[56:57], v[60:61], v[52:53], v[58:59]
	v_pk_fma_f32 v[58:59], v[62:63], v[54:55], v[56:57]
	v_pk_fma_f32 v[16:17], v[44:45], v[68:69], 0 op_sel_hi:[1,1,0]
	v_pk_fma_f32 v[18:19], v[46:47], v[70:71], v[16:17]
	v_add_f32_e32 v56, v58, v59
	v_pk_fma_f32 v[12:13], v[24:25], v[52:53], v[18:19]
	v_pk_fma_f32 v[14:15], v[26:27], v[54:55], v[12:13]
	v_add_f32_dpp v56, v56, v56 quad_perm:[1,0,3,2] row_mask:0xf bank_mask:0xf bound_ctrl:1
	s_nop 0
	v_add_f32_dpp v56, v56, v56 quad_perm:[2,3,0,1] row_mask:0xf bank_mask:0xf bound_ctrl:1
	v_add_f32_e32 v12, v14, v15
	ds_write_b32 v132, v12
	v_add_f32_dpp v56, v56, v56 row_half_mirror row_mask:0xf bank_mask:0xf bound_ctrl:1
	s_waitcnt lgkmcnt(7)
; template <int R, int DEFY> __forceinline__
; __device__ __forceinline__ void scan_chain(const Params& p, int j, int seq_start, int len, int h, int dir, int gtid, float* lds  , bool do_steps, bool do_prep, int row_base, int nrows) {
;     ...
;         auto ldstep = [&](int s, VS& d) {
;             const float* b = cb + s * 384 + seg * ES;
; #pragma unroll
;             for (int q = 0; q < NQ; ++q) {
;                 d.kk[q] = *(const f4*)(b + q * 4); d.w[q] = *(const f4*)(b + 64 + q * 4); d.ka[q] = *(const f4*)(b + 128 + q * 4);
;                 d.kd[q] = *(const f4*)(b + 192 + q * 4); d.rr[q] = *(const f4*)(b + 256 + q * 4);
;             }
; #pragma unroll
;             for (int r = 0; r < R; ++r) d.vv[r] = cb[s * 384 + 320 + row + r];
;         };
;         auto cstep = [&](int s, const VS& d) {
;             float yo[R];
; #pragma unroll
;             for (int r = 0; r < R; ++r) {
;                 f2 sacc = {0.f, 0.f}, sacc2 = {0.f, 0.f};
; #pragma unroll
;                 for (int q = 0; q < NQ; ++q) {
;                     sacc = st2[r][2 * q] * __builtin_shufflevector(d.kk[q], d.kk[q], 0, 1) + sacc;
;                     sacc2 = st2[r][2 * q + 1] * __builtin_shufflevector(d.kk[q], d.kk[q], 2, 3) + sacc2;
;                 }
;                 sacc = sacc + sacc2;
;                 float sa = sacc.x + sacc.y;
;                 sa = red8(sa);
;                 const f2 sa2 = {sa, sa}, v2 = {d.vv[r], d.vv[r]};
;                 f2 yacc = {0.f, 0.f}, yacc2 = {0.f, 0.f};
; #pragma unroll
;                 for (int q = 0; q < NQ; ++q) {
;                     const f2 t0 = v2 * __builtin_shufflevector(d.kd[q], d.kd[q], 0, 1) - sa2 * __builtin_shufflevector(d.ka[q], d.ka[q], 0, 1);
;                     const f2 t1 = v2 * __builtin_shufflevector(d.kd[q], d.kd[q], 2, 3) - sa2 * __builtin_shufflevector(d.ka[q], d.ka[q], 2, 3);
;                     st2[r][2 * q] = st2[r][2 * q] * __builtin_shufflevector(d.w[q], d.w[q], 0, 1) + t0;
;                     st2[r][2 * q + 1] = st2[r][2 * q + 1] * __builtin_shufflevector(d.w[q], d.w[q], 2, 3) + t1;
;                     yacc = st2[r][2 * q] * __builtin_shufflevector(d.rr[q], d.rr[q], 0, 1) + yacc;
;                     yacc2 = st2[r][2 * q + 1] * __builtin_shufflevector(d.rr[q], d.rr[q], 2, 3) + yacc2;
;                 }
;                 yacc = yacc + yacc2;
	v_pk_mul_f32 v[58:59], v[76:77], v[56:57] op_sel_hi:[1,0]
	v_pk_mul_f32 v[60:61], v[78:79], v[56:57] op_sel_hi:[1,0]
	s_waitcnt lgkmcnt(1)
	v_pk_fma_f32 v[58:59], v[84:85], v[130:131], v[58:59] op_sel_hi:[1,0,1] neg_lo:[0,0,1] neg_hi:[0,0,1]
	v_pk_fma_f32 v[60:61], v[86:87], v[130:131], v[60:61] op_sel_hi:[1,0,1] neg_lo:[0,0,1] neg_hi:[0,0,1]
	v_pk_mul_f32 v[62:63], v[80:81], v[56:57] op_sel_hi:[1,0]
	v_pk_mul_f32 v[56:57], v[82:83], v[56:57] op_sel_hi:[1,0]
	v_pk_fma_f32 v[148:149], v[64:65], v[68:69], v[58:59]
	v_pk_fma_f32 v[150:151], v[66:67], v[70:71], v[60:61]
	v_pk_fma_f32 v[62:63], v[88:89], v[130:131], v[62:63] op_sel_hi:[1,0,1] neg_lo:[0,0,1] neg_hi:[0,0,1]
	v_pk_fma_f32 v[56:57], v[90:91], v[130:131], v[56:57] op_sel_hi:[1,0,1] neg_lo:[0,0,1] neg_hi:[0,0,1]
	v_pk_fma_f32 v[58:59], v[136:137], v[148:149], 0 op_sel_hi:[1,1,0]
	v_pk_fma_f32 v[60:61], v[138:139], v[150:151], v[58:59]
	v_pk_fma_f32 v[152:153], v[72:73], v[52:53], v[62:63]
	v_pk_fma_f32 v[154:155], v[74:75], v[54:55], v[56:57]
	v_pk_fma_f32 v[52:53], v[140:141], v[152:153], v[60:61]
	v_pk_fma_f32 v[54:55], v[142:143], v[154:155], v[52:53]
	ds_read_b128 v[36:39], v147 offset:1536
	ds_read_b128 v[32:35], v147 offset:1552
	ds_read_b128 v[16:19], v147 offset:1792
	ds_read_b128 v[12:15], v147 offset:1808
	ds_read_b128 v[40:43], v147 offset:2048
	ds_read_b128 v[20:23], v147 offset:2064
	ds_read_b128 v[48:51], v147 offset:2304
	ds_read_b128 v[28:31], v147 offset:2320
	ds_read_b128 v[44:47], v147 offset:2560
	ds_read_b128 v[24:27], v147 offset:2576
	ds_read_b32 v128, v146 offset:1536
	s_waitcnt lgkmcnt(10)
	v_pk_fma_f32 v[136:137], v[36:37], v[148:149], 0 op_sel_hi:[1,1,0]
	v_add_f32_e32 v52, v54, v55
	ds_write_b32 v132, v52 offset:2048
	ds_read_b128 v[88:91], v147 offset:3072
	ds_read_b128 v[84:87], v147 offset:3088
	ds_read_b128 v[68:71], v147 offset:3328
	ds_read_b128 v[52:55], v147 offset:3344
	ds_read_b128 v[76:79], v147 offset:3584
	ds_read_b128 v[60:63], v147 offset:3600
	ds_read_b128 v[80:83], v147 offset:3840
	ds_read_b128 v[64:67], v147 offset:3856
	ds_read_b128 v[72:75], v147 offset:4096
	ds_read_b128 v[56:59], v147 offset:4112
	ds_read_b32 v130, v146 offset:3072
	v_pk_fma_f32 v[138:139], v[38:39], v[150:151], v[136:137]
	s_waitcnt lgkmcnt(14)
	v_pk_fma_f32 v[136:137], v[32:33], v[152:153], v[138:139]
	v_pk_fma_f32 v[138:139], v[34:35], v[154:155], v[136:137]
	s_nop 0
	s_nop 0
	v_add_f32_e32 v129, v138, v139
	s_nop 1
	v_add_f32_dpp v129, v129, v129 quad_perm:[1,0,3,2] row_mask:0xf bank_mask:0xf bound_ctrl:1
	s_nop 1
	v_add_f32_dpp v129, v129, v129 quad_perm:[2,3,0,1] row_mask:0xf bank_mask:0xf bound_ctrl:1
	s_nop 1
	v_add_f32_dpp v140, v129, v129 row_half_mirror row_mask:0xf bank_mask:0xf bound_ctrl:1
	v_pk_mul_f32 v[136:137], v[40:41], v[140:141] op_sel_hi:[1,0]
	v_pk_mul_f32 v[138:139], v[42:43], v[140:141] op_sel_hi:[1,0]
	s_waitcnt lgkmcnt(12)
	v_pk_fma_f32 v[136:137], v[48:49], v[128:129], v[136:137] op_sel_hi:[1,0,1] neg_lo:[0,0,1] neg_hi:[0,0,1]
	v_pk_fma_f32 v[138:139], v[50:51], v[128:129], v[138:139] op_sel_hi:[1,0,1] neg_lo:[0,0,1] neg_hi:[0,0,1]
	v_pk_mul_f32 v[142:143], v[20:21], v[140:141] op_sel_hi:[1,0]
	v_pk_mul_f32 v[140:141], v[22:23], v[140:141] op_sel_hi:[1,0]
	v_pk_fma_f32 v[136:137], v[16:17], v[148:149], v[136:137]
	v_pk_fma_f32 v[138:139], v[18:19], v[150:151], v[138:139]
	v_pk_fma_f32 v[142:143], v[28:29], v[128:129], v[142:143] op_sel_hi:[1,0,1] neg_lo:[0,0,1] neg_hi:[0,0,1]
	v_pk_fma_f32 v[156:157], v[30:31], v[128:129], v[140:141] op_sel_hi:[1,0,1] neg_lo:[0,0,1] neg_hi:[0,0,1]
	v_pk_fma_f32 v[148:149], v[44:45], v[136:137], 0 op_sel_hi:[1,1,0]
	v_pk_fma_f32 v[150:151], v[46:47], v[138:139], v[148:149]
	v_pk_fma_f32 v[140:141], v[12:13], v[152:153], v[142:143]
	v_pk_fma_f32 v[142:143], v[14:15], v[154:155], v[156:157]
	v_pk_fma_f32 v[148:149], v[24:25], v[140:141], v[150:151]
	v_pk_fma_f32 v[150:151], v[26:27], v[142:143], v[148:149]
	s_nop 0
	s_nop 0
	v_add_f32_e32 v129, v150, v151
	ds_write_b32 v132, v129 offset:4096
	s_cbranch_vccnz .LBB0_95
	ds_read_b128 v[36:39], v147 offset:4608
	ds_read_b128 v[32:35], v147 offset:4624
	ds_read_b128 v[16:19], v147 offset:4864
	ds_read_b128 v[12:15], v147 offset:4880
	ds_read_b128 v[40:43], v147 offset:5120
	ds_read_b128 v[20:23], v147 offset:5136
	ds_read_b128 v[48:51], v147 offset:5376
	ds_read_b128 v[28:31], v147 offset:5392
	ds_read_b128 v[44:47], v147 offset:5632
	ds_read_b128 v[24:27], v147 offset:5648
	ds_read_b32 v128, v146 offset:4608
	s_branch .LBB0_95
